# mixer phase: static priority raise for waves 0 and 4-7 (gate-prep wave and long-strip waves)
# baseline (speedup 1.0000x reference)
; #define LAS __attribute__((address_space(3)))
;     DI unsigned* fCTL() const { return (unsigned*)(ws + WS_CTL); }
; DI void phase_mixers(const Params& p, const Ctx& c, int l, int g) {
;     const int Bg = g ? 8 : 16, S = g ? 4096 : 2048, nqb = S / 128;
;     const int nml = 2 * Bg * 8, nssd = 2 * Bg * 8, natt = Bg * nqb * 2, total = nml + nssd + natt;
;     LAS int* sitem = (LAS int*)(c.lds + LDS_MAIN);
;     unsigned* ctr = c.fCTL() + l * 2 + g;
;     for (;;) {
;         if (threadIdx.x == 0) sitem[0] = (int)atomicAdd(ctr, 1u);
;         __syncthreads();
.LBB0_288:
	s_or_b64 exec, exec, s[36:37]
	s_and_b64 s[20:21], s[44:45], exec
	s_movk_i32 s2, 0x80
	s_cselect_b32 s2, 0x100, s2
	s_lshr_b32 s34, s30, 7
	s_and_b64 s[20:21], s[44:45], exec
	v_writelane_b32 v253, s2, 59
	s_cselect_b32 s2, 4, 3
	s_lshl_b32 s2, s34, s2
	s_lshl_b32 s35, s2, 1
	s_and_b64 s[20:21], s[44:45], exec
	s_movk_i32 s2, 0x100
	v_cvt_f32_ubyte0_e32 v1, s34
	s_cselect_b32 s2, 0x200, s2
	v_rcp_iflag_f32_e32 v1, v1
	v_writelane_b32 v255, s2, 6
	s_add_i32 s35, s35, s2
	s_lshl_b64 s[20:21], s[74:75], 2
	v_readlane_b32 s2, v254, 50
	s_add_u32 s20, s2, s20
	v_readlane_b32 s2, v254, 51
	s_addc_u32 s21, s2, s21
	v_writelane_b32 v255, s20, 7
	s_add_i32 s95, s30, 0xffffff00
	v_mul_f32_e32 v1, 0x4f7ffffe, v1
	v_writelane_b32 v255, s21, 8
	s_and_b64 s[20:21], s[44:45], exec
	s_movk_i32 s2, 0xfe00
	v_cvt_u32_f32_e32 v1, v1
	s_cselect_b32 s2, s2, 0xffffff00
	v_writelane_b32 v255, s2, 9
	s_cselect_b32 s2, 11, 12
	v_writelane_b32 v255, s2, 10
	s_add_i32 s2, s30, 0xffffff80
	v_writelane_b32 v255, s2, 11
	s_sub_i32 s2, 0, s34
	v_readfirstlane_b32 s20, v1
	s_mul_i32 s2, s2, s20
	s_mul_hi_u32 s2, s20, s2
	s_add_i32 s2, s20, s2
	v_writelane_b32 v255, s2, 12
	s_and_b32 s2, s30, 0x1f80
	v_writelane_b32 v255, s2, 13
	s_waitcnt lgkmcnt(0)
	s_barrier
	v_readfirstlane_b32 s2, v167
	s_nop 3
	s_cmpk_lt_u32 s2, 0x40
	s_cbranch_scc1 .Lmix_prio_set
	s_cmpk_lt_u32 s2, 0x100
	s_cbranch_scc1 .Lmix_prio_skip
.Lmix_prio_set:
	s_setprio 1
